# v38 + qproj row_rstd: 16 serialized loads issued together with one wait
# speedup vs baseline: 1.0175x; 1.0051x over previous
.LBB0_753:
	v_add_co_u32_e32 v4, vcc, 0xa000000, v2
	s_nop 1
	v_addc_co_u32_e32 v5, vcc, 0, v3, vcc
	global_load_dwordx4 v[184:187], v[4:5], off offset:3072
	global_load_dwordx4 v[188:191], v[4:5], off offset:3088
	global_load_dwordx4 v[192:195], v[4:5], off offset:3104
	global_load_dwordx4 v[196:199], v[4:5], off offset:3120
	global_load_dwordx4 v[200:203], v[4:5], off offset:3136
	global_load_dwordx4 v[204:207], v[4:5], off offset:3152
	global_load_dwordx4 v[208:211], v[4:5], off offset:3168
	global_load_dwordx4 v[212:215], v[4:5], off offset:3184
	global_load_dwordx4 v[216:219], v[4:5], off offset:3200
	global_load_dwordx4 v[220:223], v[4:5], off offset:3216
	global_load_dwordx4 v[224:227], v[4:5], off offset:3232
	global_load_dwordx4 v[240:243], v[4:5], off offset:3248
	global_load_dwordx4 v[244:247], v[4:5], off offset:3264
	global_load_dwordx4 v[248:251], v[4:5], off offset:3280
	global_load_dwordx4 v[252:255], v[4:5], off offset:3296
	global_load_dwordx4 v[10:13], v[4:5], off offset:3312
	v_mov_b32_e32 v14, 0
	v_mov_b32_e32 v15, 0
	v_mov_b32_e32 v16, 0
	s_waitcnt vmcnt(0)
	v_lshlrev_b32_e32 v17, 16, v184
	v_and_b32_e32 v9, 0xffff0000, v184
	v_fma_f32 v8, v17, v17, v8
	v_fma_f32 v8, v9, v9, v8
	v_lshlrev_b32_e32 v17, 16, v185
	v_and_b32_e32 v9, 0xffff0000, v185
	v_fma_f32 v14, v17, v17, v14
	v_fma_f32 v14, v9, v9, v14
	v_lshlrev_b32_e32 v17, 16, v186
	v_and_b32_e32 v9, 0xffff0000, v186
	v_fma_f32 v15, v17, v17, v15
	v_fma_f32 v15, v9, v9, v15
	v_lshlrev_b32_e32 v17, 16, v187
	v_and_b32_e32 v9, 0xffff0000, v187
	v_fma_f32 v16, v17, v17, v16
	v_fma_f32 v16, v9, v9, v16
	v_lshlrev_b32_e32 v17, 16, v188
	v_and_b32_e32 v9, 0xffff0000, v188
	v_fma_f32 v8, v17, v17, v8
	v_fma_f32 v8, v9, v9, v8
	v_lshlrev_b32_e32 v17, 16, v189
	v_and_b32_e32 v9, 0xffff0000, v189
	v_fma_f32 v14, v17, v17, v14
	v_fma_f32 v14, v9, v9, v14
	v_lshlrev_b32_e32 v17, 16, v190
	v_and_b32_e32 v9, 0xffff0000, v190
	v_fma_f32 v15, v17, v17, v15
	v_fma_f32 v15, v9, v9, v15
	v_lshlrev_b32_e32 v17, 16, v191
	v_and_b32_e32 v9, 0xffff0000, v191
	v_fma_f32 v16, v17, v17, v16
	v_fma_f32 v16, v9, v9, v16
	v_lshlrev_b32_e32 v17, 16, v192
	v_and_b32_e32 v9, 0xffff0000, v192
	v_fma_f32 v8, v17, v17, v8
	v_fma_f32 v8, v9, v9, v8
	v_lshlrev_b32_e32 v17, 16, v193
	v_and_b32_e32 v9, 0xffff0000, v193
	v_fma_f32 v14, v17, v17, v14
	v_fma_f32 v14, v9, v9, v14
	v_lshlrev_b32_e32 v17, 16, v194
	v_and_b32_e32 v9, 0xffff0000, v194
	v_fma_f32 v15, v17, v17, v15
	v_fma_f32 v15, v9, v9, v15
	v_lshlrev_b32_e32 v17, 16, v195
	v_and_b32_e32 v9, 0xffff0000, v195
	v_fma_f32 v16, v17, v17, v16
	v_fma_f32 v16, v9, v9, v16
	v_lshlrev_b32_e32 v17, 16, v196
	v_and_b32_e32 v9, 0xffff0000, v196
	v_fma_f32 v8, v17, v17, v8
	v_fma_f32 v8, v9, v9, v8
	v_lshlrev_b32_e32 v17, 16, v197
	v_and_b32_e32 v9, 0xffff0000, v197
	v_fma_f32 v14, v17, v17, v14
	v_fma_f32 v14, v9, v9, v14
	v_lshlrev_b32_e32 v17, 16, v198
	v_and_b32_e32 v9, 0xffff0000, v198
	v_fma_f32 v15, v17, v17, v15
	v_fma_f32 v15, v9, v9, v15
	v_lshlrev_b32_e32 v17, 16, v199
	v_and_b32_e32 v9, 0xffff0000, v199
	v_fma_f32 v16, v17, v17, v16
	v_fma_f32 v16, v9, v9, v16
	v_lshlrev_b32_e32 v17, 16, v200
	v_and_b32_e32 v9, 0xffff0000, v200
	v_fma_f32 v8, v17, v17, v8
	v_fma_f32 v8, v9, v9, v8
	v_lshlrev_b32_e32 v17, 16, v201
	v_and_b32_e32 v9, 0xffff0000, v201
	v_fma_f32 v14, v17, v17, v14
	v_fma_f32 v14, v9, v9, v14
	v_lshlrev_b32_e32 v17, 16, v202
	v_and_b32_e32 v9, 0xffff0000, v202
	v_fma_f32 v15, v17, v17, v15
	v_fma_f32 v15, v9, v9, v15
	v_lshlrev_b32_e32 v17, 16, v203
	v_and_b32_e32 v9, 0xffff0000, v203
	v_fma_f32 v16, v17, v17, v16
	v_fma_f32 v16, v9, v9, v16
	v_lshlrev_b32_e32 v17, 16, v204
	v_and_b32_e32 v9, 0xffff0000, v204
	v_fma_f32 v8, v17, v17, v8
	v_fma_f32 v8, v9, v9, v8
	v_lshlrev_b32_e32 v17, 16, v205
	v_and_b32_e32 v9, 0xffff0000, v205
	v_fma_f32 v14, v17, v17, v14
	v_fma_f32 v14, v9, v9, v14
	v_lshlrev_b32_e32 v17, 16, v206
	v_and_b32_e32 v9, 0xffff0000, v206
	v_fma_f32 v15, v17, v17, v15
	v_fma_f32 v15, v9, v9, v15
	v_lshlrev_b32_e32 v17, 16, v207
	v_and_b32_e32 v9, 0xffff0000, v207
	v_fma_f32 v16, v17, v17, v16
	v_fma_f32 v16, v9, v9, v16
	v_lshlrev_b32_e32 v17, 16, v208
	v_and_b32_e32 v9, 0xffff0000, v208
	v_fma_f32 v8, v17, v17, v8
	v_fma_f32 v8, v9, v9, v8
	v_lshlrev_b32_e32 v17, 16, v209
	v_and_b32_e32 v9, 0xffff0000, v209
	v_fma_f32 v14, v17, v17, v14
	v_fma_f32 v14, v9, v9, v14
	v_lshlrev_b32_e32 v17, 16, v210
	v_and_b32_e32 v9, 0xffff0000, v210
	v_fma_f32 v15, v17, v17, v15
	v_fma_f32 v15, v9, v9, v15
	v_lshlrev_b32_e32 v17, 16, v211
	v_and_b32_e32 v9, 0xffff0000, v211
	v_fma_f32 v16, v17, v17, v16
	v_fma_f32 v16, v9, v9, v16
	v_lshlrev_b32_e32 v17, 16, v212
	v_and_b32_e32 v9, 0xffff0000, v212
	v_fma_f32 v8, v17, v17, v8
	v_fma_f32 v8, v9, v9, v8
	v_lshlrev_b32_e32 v17, 16, v213
	v_and_b32_e32 v9, 0xffff0000, v213
	v_fma_f32 v14, v17, v17, v14
	v_fma_f32 v14, v9, v9, v14
	v_lshlrev_b32_e32 v17, 16, v214
	v_and_b32_e32 v9, 0xffff0000, v214
	v_fma_f32 v15, v17, v17, v15
	v_fma_f32 v15, v9, v9, v15
	v_lshlrev_b32_e32 v17, 16, v215
	v_and_b32_e32 v9, 0xffff0000, v215
	v_fma_f32 v16, v17, v17, v16
	v_fma_f32 v16, v9, v9, v16
	v_lshlrev_b32_e32 v17, 16, v216
	v_and_b32_e32 v9, 0xffff0000, v216
	v_fma_f32 v8, v17, v17, v8
	v_fma_f32 v8, v9, v9, v8
	v_lshlrev_b32_e32 v17, 16, v217
	v_and_b32_e32 v9, 0xffff0000, v217
	v_fma_f32 v14, v17, v17, v14
	v_fma_f32 v14, v9, v9, v14
	v_lshlrev_b32_e32 v17, 16, v218
	v_and_b32_e32 v9, 0xffff0000, v218
	v_fma_f32 v15, v17, v17, v15
	v_fma_f32 v15, v9, v9, v15
	v_lshlrev_b32_e32 v17, 16, v219
	v_and_b32_e32 v9, 0xffff0000, v219
	v_fma_f32 v16, v17, v17, v16
	v_fma_f32 v16, v9, v9, v16
	v_lshlrev_b32_e32 v17, 16, v220
	v_and_b32_e32 v9, 0xffff0000, v220
	v_fma_f32 v8, v17, v17, v8
	v_fma_f32 v8, v9, v9, v8
	v_lshlrev_b32_e32 v17, 16, v221
	v_and_b32_e32 v9, 0xffff0000, v221
	v_fma_f32 v14, v17, v17, v14
	v_fma_f32 v14, v9, v9, v14
	v_lshlrev_b32_e32 v17, 16, v222
	v_and_b32_e32 v9, 0xffff0000, v222
	v_fma_f32 v15, v17, v17, v15
	v_fma_f32 v15, v9, v9, v15
	v_lshlrev_b32_e32 v17, 16, v223
	v_and_b32_e32 v9, 0xffff0000, v223
	v_fma_f32 v16, v17, v17, v16
	v_fma_f32 v16, v9, v9, v16
	v_lshlrev_b32_e32 v17, 16, v224
	v_and_b32_e32 v9, 0xffff0000, v224
	v_fma_f32 v8, v17, v17, v8
	v_fma_f32 v8, v9, v9, v8
	v_lshlrev_b32_e32 v17, 16, v225
	v_and_b32_e32 v9, 0xffff0000, v225
	v_fma_f32 v14, v17, v17, v14
	v_fma_f32 v14, v9, v9, v14
	v_lshlrev_b32_e32 v17, 16, v226
	v_and_b32_e32 v9, 0xffff0000, v226
	v_fma_f32 v15, v17, v17, v15
	v_fma_f32 v15, v9, v9, v15
	v_lshlrev_b32_e32 v17, 16, v227
	v_and_b32_e32 v9, 0xffff0000, v227
	v_fma_f32 v16, v17, v17, v16
	v_fma_f32 v16, v9, v9, v16
	v_lshlrev_b32_e32 v17, 16, v240
	v_and_b32_e32 v9, 0xffff0000, v240
	v_fma_f32 v8, v17, v17, v8
	v_fma_f32 v8, v9, v9, v8
	v_lshlrev_b32_e32 v17, 16, v241
	v_and_b32_e32 v9, 0xffff0000, v241
	v_fma_f32 v14, v17, v17, v14
	v_fma_f32 v14, v9, v9, v14
	v_lshlrev_b32_e32 v17, 16, v242
	v_and_b32_e32 v9, 0xffff0000, v242
	v_fma_f32 v15, v17, v17, v15
	v_fma_f32 v15, v9, v9, v15
	v_lshlrev_b32_e32 v17, 16, v243
	v_and_b32_e32 v9, 0xffff0000, v243
	v_fma_f32 v16, v17, v17, v16
	v_fma_f32 v16, v9, v9, v16
	v_lshlrev_b32_e32 v17, 16, v244
	v_and_b32_e32 v9, 0xffff0000, v244
	v_fma_f32 v8, v17, v17, v8
	v_fma_f32 v8, v9, v9, v8
	v_lshlrev_b32_e32 v17, 16, v245
	v_and_b32_e32 v9, 0xffff0000, v245
	v_fma_f32 v14, v17, v17, v14
	v_fma_f32 v14, v9, v9, v14
	v_lshlrev_b32_e32 v17, 16, v246
	v_and_b32_e32 v9, 0xffff0000, v246
	v_fma_f32 v15, v17, v17, v15
	v_fma_f32 v15, v9, v9, v15
	v_lshlrev_b32_e32 v17, 16, v247
	v_and_b32_e32 v9, 0xffff0000, v247
	v_fma_f32 v16, v17, v17, v16
	v_fma_f32 v16, v9, v9, v16
	v_lshlrev_b32_e32 v17, 16, v248
	v_and_b32_e32 v9, 0xffff0000, v248
	v_fma_f32 v8, v17, v17, v8
	v_fma_f32 v8, v9, v9, v8
	v_lshlrev_b32_e32 v17, 16, v249
	v_and_b32_e32 v9, 0xffff0000, v249
	v_fma_f32 v14, v17, v17, v14
	v_fma_f32 v14, v9, v9, v14
	v_lshlrev_b32_e32 v17, 16, v250
	v_and_b32_e32 v9, 0xffff0000, v250
	v_fma_f32 v15, v17, v17, v15
	v_fma_f32 v15, v9, v9, v15
	v_lshlrev_b32_e32 v17, 16, v251
	v_and_b32_e32 v9, 0xffff0000, v251
	v_fma_f32 v16, v17, v17, v16
	v_fma_f32 v16, v9, v9, v16
	v_lshlrev_b32_e32 v17, 16, v252
	v_and_b32_e32 v9, 0xffff0000, v252
	v_fma_f32 v8, v17, v17, v8
	v_fma_f32 v8, v9, v9, v8
	v_lshlrev_b32_e32 v17, 16, v253
	v_and_b32_e32 v9, 0xffff0000, v253
	v_fma_f32 v14, v17, v17, v14
	v_fma_f32 v14, v9, v9, v14
	v_lshlrev_b32_e32 v17, 16, v254
	v_and_b32_e32 v9, 0xffff0000, v254
	v_fma_f32 v15, v17, v17, v15
	v_fma_f32 v15, v9, v9, v15
	v_lshlrev_b32_e32 v17, 16, v255
	v_and_b32_e32 v9, 0xffff0000, v255
	v_fma_f32 v16, v17, v17, v16
	v_fma_f32 v16, v9, v9, v16
	v_lshlrev_b32_e32 v17, 16, v10
	v_and_b32_e32 v9, 0xffff0000, v10
	v_fma_f32 v8, v17, v17, v8
	v_fma_f32 v8, v9, v9, v8
	v_lshlrev_b32_e32 v17, 16, v11
	v_and_b32_e32 v9, 0xffff0000, v11
	v_fma_f32 v14, v17, v17, v14
	v_fma_f32 v14, v9, v9, v14
	v_lshlrev_b32_e32 v17, 16, v12
	v_and_b32_e32 v9, 0xffff0000, v12
	v_fma_f32 v15, v17, v17, v15
	v_fma_f32 v15, v9, v9, v15
	v_lshlrev_b32_e32 v17, 16, v13
	v_and_b32_e32 v9, 0xffff0000, v13
	v_fma_f32 v16, v17, v17, v16
	v_fma_f32 v16, v9, v9, v16
	v_add_f32_e32 v8, v8, v14
	v_add_f32_e32 v15, v15, v16
	v_add_f32_e32 v8, v8, v15
	v_and_b32_e32 v3, 64, v170
	v_xor_b32_e32 v2, 1, v170
	v_add_u32_e32 v3, 64, v3
	v_cmp_lt_i32_e32 vcc, v2, v3
	s_nop 1
	v_cndmask_b32_e32 v2, v170, v2, vcc
	v_lshlrev_b32_e32 v2, 2, v2
	ds_bpermute_b32 v2, v2, v8
	v_cmp_eq_u32_e32 vcc, 0, v7
	s_and_saveexec_b64 s[0:1], vcc
	s_cbranch_execz .LBB0_756
	s_waitcnt lgkmcnt(0)
	v_add_f32_e32 v2, v8, v2
	v_fmamk_f32 v2, v2, 0x3b800000, v137
	v_mul_f32_e32 v3, 0x4b800000, v2
	v_cmp_gt_f32_e32 vcc, s87, v2
	s_nop 1
	v_cndmask_b32_e32 v2, v2, v3, vcc
	v_rsq_f32_e32 v2, v2
	s_nop 0
	v_mul_f32_e32 v3, 0x45800000, v2
	v_cndmask_b32_e32 v2, v2, v3, vcc
	v_lshl_add_u32 v3, v6, 2, s92
	ds_write_b32 v3, v2 offset:36864

.LBB0_1748:
	v_add_co_u32_e32 v4, vcc, 0xa000000, v2
	s_nop 1
	v_addc_co_u32_e32 v5, vcc, 0, v3, vcc
	global_load_dwordx4 v[184:187], v[4:5], off offset:3072
	global_load_dwordx4 v[188:191], v[4:5], off offset:3088
	global_load_dwordx4 v[192:195], v[4:5], off offset:3104
	global_load_dwordx4 v[196:199], v[4:5], off offset:3120
	global_load_dwordx4 v[200:203], v[4:5], off offset:3136
	global_load_dwordx4 v[204:207], v[4:5], off offset:3152
	global_load_dwordx4 v[208:211], v[4:5], off offset:3168
	global_load_dwordx4 v[212:215], v[4:5], off offset:3184
	global_load_dwordx4 v[216:219], v[4:5], off offset:3200
	global_load_dwordx4 v[220:223], v[4:5], off offset:3216
	global_load_dwordx4 v[224:227], v[4:5], off offset:3232
	global_load_dwordx4 v[240:243], v[4:5], off offset:3248
	global_load_dwordx4 v[244:247], v[4:5], off offset:3264
	global_load_dwordx4 v[248:251], v[4:5], off offset:3280
	global_load_dwordx4 v[252:255], v[4:5], off offset:3296
	global_load_dwordx4 v[10:13], v[4:5], off offset:3312
	v_mov_b32_e32 v14, 0
	v_mov_b32_e32 v15, 0
	v_mov_b32_e32 v16, 0
	s_waitcnt vmcnt(0)
	v_lshlrev_b32_e32 v17, 16, v184
	v_and_b32_e32 v9, 0xffff0000, v184
	v_fma_f32 v8, v17, v17, v8
	v_fma_f32 v8, v9, v9, v8
	v_lshlrev_b32_e32 v17, 16, v185
	v_and_b32_e32 v9, 0xffff0000, v185
	v_fma_f32 v14, v17, v17, v14
	v_fma_f32 v14, v9, v9, v14
	v_lshlrev_b32_e32 v17, 16, v186
	v_and_b32_e32 v9, 0xffff0000, v186
	v_fma_f32 v15, v17, v17, v15
	v_fma_f32 v15, v9, v9, v15
	v_lshlrev_b32_e32 v17, 16, v187
	v_and_b32_e32 v9, 0xffff0000, v187
	v_fma_f32 v16, v17, v17, v16
	v_fma_f32 v16, v9, v9, v16
	v_lshlrev_b32_e32 v17, 16, v188
	v_and_b32_e32 v9, 0xffff0000, v188
	v_fma_f32 v8, v17, v17, v8
	v_fma_f32 v8, v9, v9, v8
	v_lshlrev_b32_e32 v17, 16, v189
	v_and_b32_e32 v9, 0xffff0000, v189
	v_fma_f32 v14, v17, v17, v14
	v_fma_f32 v14, v9, v9, v14
	v_lshlrev_b32_e32 v17, 16, v190
	v_and_b32_e32 v9, 0xffff0000, v190
	v_fma_f32 v15, v17, v17, v15
	v_fma_f32 v15, v9, v9, v15
	v_lshlrev_b32_e32 v17, 16, v191
	v_and_b32_e32 v9, 0xffff0000, v191
	v_fma_f32 v16, v17, v17, v16
	v_fma_f32 v16, v9, v9, v16
	v_lshlrev_b32_e32 v17, 16, v192
	v_and_b32_e32 v9, 0xffff0000, v192
	v_fma_f32 v8, v17, v17, v8
	v_fma_f32 v8, v9, v9, v8
	v_lshlrev_b32_e32 v17, 16, v193
	v_and_b32_e32 v9, 0xffff0000, v193
	v_fma_f32 v14, v17, v17, v14
	v_fma_f32 v14, v9, v9, v14
	v_lshlrev_b32_e32 v17, 16, v194
	v_and_b32_e32 v9, 0xffff0000, v194
	v_fma_f32 v15, v17, v17, v15
	v_fma_f32 v15, v9, v9, v15
	v_lshlrev_b32_e32 v17, 16, v195
	v_and_b32_e32 v9, 0xffff0000, v195
	v_fma_f32 v16, v17, v17, v16
	v_fma_f32 v16, v9, v9, v16
	v_lshlrev_b32_e32 v17, 16, v196
	v_and_b32_e32 v9, 0xffff0000, v196
	v_fma_f32 v8, v17, v17, v8
	v_fma_f32 v8, v9, v9, v8
	v_lshlrev_b32_e32 v17, 16, v197
	v_and_b32_e32 v9, 0xffff0000, v197
	v_fma_f32 v14, v17, v17, v14
	v_fma_f32 v14, v9, v9, v14
	v_lshlrev_b32_e32 v17, 16, v198
	v_and_b32_e32 v9, 0xffff0000, v198
	v_fma_f32 v15, v17, v17, v15
	v_fma_f32 v15, v9, v9, v15
	v_lshlrev_b32_e32 v17, 16, v199
	v_and_b32_e32 v9, 0xffff0000, v199
	v_fma_f32 v16, v17, v17, v16
	v_fma_f32 v16, v9, v9, v16
	v_lshlrev_b32_e32 v17, 16, v200
	v_and_b32_e32 v9, 0xffff0000, v200
	v_fma_f32 v8, v17, v17, v8
	v_fma_f32 v8, v9, v9, v8
	v_lshlrev_b32_e32 v17, 16, v201
	v_and_b32_e32 v9, 0xffff0000, v201
	v_fma_f32 v14, v17, v17, v14
	v_fma_f32 v14, v9, v9, v14
	v_lshlrev_b32_e32 v17, 16, v202
	v_and_b32_e32 v9, 0xffff0000, v202
	v_fma_f32 v15, v17, v17, v15
	v_fma_f32 v15, v9, v9, v15
	v_lshlrev_b32_e32 v17, 16, v203
	v_and_b32_e32 v9, 0xffff0000, v203
	v_fma_f32 v16, v17, v17, v16
	v_fma_f32 v16, v9, v9, v16
	v_lshlrev_b32_e32 v17, 16, v204
	v_and_b32_e32 v9, 0xffff0000, v204
	v_fma_f32 v8, v17, v17, v8
	v_fma_f32 v8, v9, v9, v8
	v_lshlrev_b32_e32 v17, 16, v205
	v_and_b32_e32 v9, 0xffff0000, v205
	v_fma_f32 v14, v17, v17, v14
	v_fma_f32 v14, v9, v9, v14
	v_lshlrev_b32_e32 v17, 16, v206
	v_and_b32_e32 v9, 0xffff0000, v206
	v_fma_f32 v15, v17, v17, v15
	v_fma_f32 v15, v9, v9, v15
	v_lshlrev_b32_e32 v17, 16, v207
	v_and_b32_e32 v9, 0xffff0000, v207
	v_fma_f32 v16, v17, v17, v16
	v_fma_f32 v16, v9, v9, v16
	v_lshlrev_b32_e32 v17, 16, v208
	v_and_b32_e32 v9, 0xffff0000, v208
	v_fma_f32 v8, v17, v17, v8
	v_fma_f32 v8, v9, v9, v8
	v_lshlrev_b32_e32 v17, 16, v209
	v_and_b32_e32 v9, 0xffff0000, v209
	v_fma_f32 v14, v17, v17, v14
	v_fma_f32 v14, v9, v9, v14
	v_lshlrev_b32_e32 v17, 16, v210
	v_and_b32_e32 v9, 0xffff0000, v210
	v_fma_f32 v15, v17, v17, v15
	v_fma_f32 v15, v9, v9, v15
	v_lshlrev_b32_e32 v17, 16, v211
	v_and_b32_e32 v9, 0xffff0000, v211
	v_fma_f32 v16, v17, v17, v16
	v_fma_f32 v16, v9, v9, v16
	v_lshlrev_b32_e32 v17, 16, v212
	v_and_b32_e32 v9, 0xffff0000, v212
	v_fma_f32 v8, v17, v17, v8
	v_fma_f32 v8, v9, v9, v8
	v_lshlrev_b32_e32 v17, 16, v213
	v_and_b32_e32 v9, 0xffff0000, v213
	v_fma_f32 v14, v17, v17, v14
	v_fma_f32 v14, v9, v9, v14
	v_lshlrev_b32_e32 v17, 16, v214
	v_and_b32_e32 v9, 0xffff0000, v214
	v_fma_f32 v15, v17, v17, v15
	v_fma_f32 v15, v9, v9, v15
	v_lshlrev_b32_e32 v17, 16, v215
	v_and_b32_e32 v9, 0xffff0000, v215
	v_fma_f32 v16, v17, v17, v16
	v_fma_f32 v16, v9, v9, v16
	v_lshlrev_b32_e32 v17, 16, v216
	v_and_b32_e32 v9, 0xffff0000, v216
	v_fma_f32 v8, v17, v17, v8
	v_fma_f32 v8, v9, v9, v8
	v_lshlrev_b32_e32 v17, 16, v217
	v_and_b32_e32 v9, 0xffff0000, v217
	v_fma_f32 v14, v17, v17, v14
	v_fma_f32 v14, v9, v9, v14
	v_lshlrev_b32_e32 v17, 16, v218
	v_and_b32_e32 v9, 0xffff0000, v218
	v_fma_f32 v15, v17, v17, v15
	v_fma_f32 v15, v9, v9, v15
	v_lshlrev_b32_e32 v17, 16, v219
	v_and_b32_e32 v9, 0xffff0000, v219
	v_fma_f32 v16, v17, v17, v16
	v_fma_f32 v16, v9, v9, v16
	v_lshlrev_b32_e32 v17, 16, v220
	v_and_b32_e32 v9, 0xffff0000, v220
	v_fma_f32 v8, v17, v17, v8
	v_fma_f32 v8, v9, v9, v8
	v_lshlrev_b32_e32 v17, 16, v221
	v_and_b32_e32 v9, 0xffff0000, v221
	v_fma_f32 v14, v17, v17, v14
	v_fma_f32 v14, v9, v9, v14
	v_lshlrev_b32_e32 v17, 16, v222
	v_and_b32_e32 v9, 0xffff0000, v222
	v_fma_f32 v15, v17, v17, v15
	v_fma_f32 v15, v9, v9, v15
	v_lshlrev_b32_e32 v17, 16, v223
	v_and_b32_e32 v9, 0xffff0000, v223
	v_fma_f32 v16, v17, v17, v16
	v_fma_f32 v16, v9, v9, v16
	v_lshlrev_b32_e32 v17, 16, v224
	v_and_b32_e32 v9, 0xffff0000, v224
	v_fma_f32 v8, v17, v17, v8
	v_fma_f32 v8, v9, v9, v8
	v_lshlrev_b32_e32 v17, 16, v225
	v_and_b32_e32 v9, 0xffff0000, v225
	v_fma_f32 v14, v17, v17, v14
	v_fma_f32 v14, v9, v9, v14
	v_lshlrev_b32_e32 v17, 16, v226
	v_and_b32_e32 v9, 0xffff0000, v226
	v_fma_f32 v15, v17, v17, v15
	v_fma_f32 v15, v9, v9, v15
	v_lshlrev_b32_e32 v17, 16, v227
	v_and_b32_e32 v9, 0xffff0000, v227
	v_fma_f32 v16, v17, v17, v16
	v_fma_f32 v16, v9, v9, v16
	v_lshlrev_b32_e32 v17, 16, v240
	v_and_b32_e32 v9, 0xffff0000, v240
	v_fma_f32 v8, v17, v17, v8
	v_fma_f32 v8, v9, v9, v8
	v_lshlrev_b32_e32 v17, 16, v241
	v_and_b32_e32 v9, 0xffff0000, v241
	v_fma_f32 v14, v17, v17, v14
	v_fma_f32 v14, v9, v9, v14
	v_lshlrev_b32_e32 v17, 16, v242
	v_and_b32_e32 v9, 0xffff0000, v242
	v_fma_f32 v15, v17, v17, v15
	v_fma_f32 v15, v9, v9, v15
	v_lshlrev_b32_e32 v17, 16, v243
	v_and_b32_e32 v9, 0xffff0000, v243
	v_fma_f32 v16, v17, v17, v16
	v_fma_f32 v16, v9, v9, v16
	v_lshlrev_b32_e32 v17, 16, v244
	v_and_b32_e32 v9, 0xffff0000, v244
	v_fma_f32 v8, v17, v17, v8
	v_fma_f32 v8, v9, v9, v8
	v_lshlrev_b32_e32 v17, 16, v245
	v_and_b32_e32 v9, 0xffff0000, v245
	v_fma_f32 v14, v17, v17, v14
	v_fma_f32 v14, v9, v9, v14
	v_lshlrev_b32_e32 v17, 16, v246
	v_and_b32_e32 v9, 0xffff0000, v246
	v_fma_f32 v15, v17, v17, v15
	v_fma_f32 v15, v9, v9, v15
	v_lshlrev_b32_e32 v17, 16, v247
	v_and_b32_e32 v9, 0xffff0000, v247
	v_fma_f32 v16, v17, v17, v16
	v_fma_f32 v16, v9, v9, v16
	v_lshlrev_b32_e32 v17, 16, v248
	v_and_b32_e32 v9, 0xffff0000, v248
	v_fma_f32 v8, v17, v17, v8
	v_fma_f32 v8, v9, v9, v8
	v_lshlrev_b32_e32 v17, 16, v249
	v_and_b32_e32 v9, 0xffff0000, v249
	v_fma_f32 v14, v17, v17, v14
	v_fma_f32 v14, v9, v9, v14
	v_lshlrev_b32_e32 v17, 16, v250
	v_and_b32_e32 v9, 0xffff0000, v250
	v_fma_f32 v15, v17, v17, v15
	v_fma_f32 v15, v9, v9, v15
	v_lshlrev_b32_e32 v17, 16, v251
	v_and_b32_e32 v9, 0xffff0000, v251
	v_fma_f32 v16, v17, v17, v16
	v_fma_f32 v16, v9, v9, v16
	v_lshlrev_b32_e32 v17, 16, v252
	v_and_b32_e32 v9, 0xffff0000, v252
	v_fma_f32 v8, v17, v17, v8
	v_fma_f32 v8, v9, v9, v8
	v_lshlrev_b32_e32 v17, 16, v253
	v_and_b32_e32 v9, 0xffff0000, v253
	v_fma_f32 v14, v17, v17, v14
	v_fma_f32 v14, v9, v9, v14
	v_lshlrev_b32_e32 v17, 16, v254
	v_and_b32_e32 v9, 0xffff0000, v254
	v_fma_f32 v15, v17, v17, v15
	v_fma_f32 v15, v9, v9, v15
	v_lshlrev_b32_e32 v17, 16, v255
	v_and_b32_e32 v9, 0xffff0000, v255
	v_fma_f32 v16, v17, v17, v16
	v_fma_f32 v16, v9, v9, v16
	v_lshlrev_b32_e32 v17, 16, v10
	v_and_b32_e32 v9, 0xffff0000, v10
	v_fma_f32 v8, v17, v17, v8
	v_fma_f32 v8, v9, v9, v8
	v_lshlrev_b32_e32 v17, 16, v11
	v_and_b32_e32 v9, 0xffff0000, v11
	v_fma_f32 v14, v17, v17, v14
	v_fma_f32 v14, v9, v9, v14
	v_lshlrev_b32_e32 v17, 16, v12
	v_and_b32_e32 v9, 0xffff0000, v12
	v_fma_f32 v15, v17, v17, v15
	v_fma_f32 v15, v9, v9, v15
	v_lshlrev_b32_e32 v17, 16, v13
	v_and_b32_e32 v9, 0xffff0000, v13
	v_fma_f32 v16, v17, v17, v16
	v_fma_f32 v16, v9, v9, v16
	v_add_f32_e32 v8, v8, v14
	v_add_f32_e32 v15, v15, v16
	v_add_f32_e32 v8, v8, v15
	v_and_b32_e32 v3, 64, v170
	v_xor_b32_e32 v2, 1, v170
	v_add_u32_e32 v3, 64, v3
	v_cmp_lt_i32_e32 vcc, v2, v3
	s_nop 1
	v_cndmask_b32_e32 v2, v170, v2, vcc
	v_lshlrev_b32_e32 v2, 2, v2
	ds_bpermute_b32 v2, v2, v8
	v_cmp_eq_u32_e32 vcc, 0, v7
	s_and_saveexec_b64 s[0:1], vcc
	s_cbranch_execz .LBB0_1751
	s_waitcnt lgkmcnt(0)
	v_add_f32_e32 v2, v8, v2
	v_fmamk_f32 v2, v2, 0x3b800000, v137
	s_mov_b32 s2, 0x800000
	v_mul_f32_e32 v3, 0x4b800000, v2
	v_cmp_gt_f32_e32 vcc, s2, v2
	s_nop 1
	v_cndmask_b32_e32 v2, v2, v3, vcc
	v_rsq_f32_e32 v2, v2
	s_nop 0
	v_mul_f32_e32 v3, 0x45800000, v2
	v_cndmask_b32_e32 v2, v2, v3, vcc
	v_lshl_add_u32 v3, v6, 2, s92
	ds_write_b32 v3, v2 offset:36864
